# accumulator-chained activation-major MFMA order also in the two regular clusters of the P7 K-loop (its register-shifted clusters untouched)
# baseline (speedup 1.0000x reference)
; #define PG8_STAGE(bufoff, gbase, voff) do { _Pragma("unroll") for (int _i = 0; _i < 2; ++_i) \
;         asm volatile("s_mov_b32 m0, %2\n\ts_nop 0\n\tglobal_load_lds_dwordx4 %0, %1" :: "v"((voff)[_i]), "s"((const char*)(gbase)), "s"(ldsbase + (unsigned)(bufoff) + ldsw + (unsigned)_i * 8192u) : "memory", "m0"); } while (0)
; #define PG8_LDA(dst, b, h) do { _Pragma("unroll") for (int m = 0; m < 4; ++m) _Pragma("unroll") for (int k = 0; k < 2; ++k) dst[m][k] = *(const PG8_LAS bf16x8*)(lds + PG8_SA(b, h) + aoff + m * 2048 + k * 1024); } while (0)
; #define PG8_LDB(dst, b, h) do { _Pragma("unroll") for (int n = 0; n < 2; ++n) _Pragma("unroll") for (int k = 0; k < 2; ++k) dst[n][k] = *(const PG8_LAS bf16x8*)(lds + PG8_SB(b, h) + boff + n * 2048 + k * 1024); } while (0)
; #define PG8_MMA(ai, bj, At, Bt) do { __builtin_amdgcn_s_setprio(1); _Pragma("unroll") for (int m = 0; m < 4; ++m) _Pragma("unroll") for (int n = 0; n < 2; ++n) _Pragma("unroll") for (int k = 0; k < 2; ++k) \
;         acc[ai][bj][m][n] = __builtin_amdgcn_mfma_f32_16x16x32_bf16(Bt[n][k], At[m][k], acc[ai][bj][m][n], 0, 0, 0); __builtin_amdgcn_s_setprio(0); } while (0)
; #define PG8_WAIT_V(n) asm volatile("s_waitcnt vmcnt(" #n ")" ::: "memory")
; template <class Epi, class Sched, bool ALIGN_EPI = false, bool SP2 = false>
; __device__ __forceinline__ void gemm_phase(PG8_LAS unsigned char* lds, const Gemm g, const Sched& S, const Epi& E) {
;     ...
;             const char* a1 = cA + (size_t)(t + 1) * kstep;
;             const char* a2 = last ? nA : cA + (size_t)(t + 2) * kstep; const char* b2 = last ? nB : cB + (size_t)(t + 2) * kstep;
;             const char* a3 = a2 + kstep; const char* b3 = b2 + kstep;
;             if (last && has_next) S.a_ready(nxt);
;             if constexpr (epi_has_mid<Epi>::value) { if (t == Epi::MID_T) E.mid(acc, cur, wr, wc, fr, fq); }
;             if constexpr (SP2) {
;             PG8_LDB(B0, 0, 0); PG8_LDB(B1, 0, 1); PG8_SCHED; PG8_LDA(At, 0, 0); PG8_STAGE(PG8_SA(1, 1), a1 + hstep, voffA);
;             PG8_WAIT_V(8); PG8_WAIT_L(0); PG8_BAR; PG8_MMA(0, 0, At, B0); PG8_MMA(0, 1, At, B1); PG8_BAR; PG8_SCHED;
;             PG8_LDA(At, 0, 1); PG8_STAGE(PG8_SB(0, 0), b2, voffB); PG8_STAGE(PG8_SB(0, 1), b2 + hstep, voffB); PG8_STAGE(PG8_SA(0, 0), a2, voffA);
;             PG8_WAIT_V(8); PG8_WAIT_L(0); PG8_BAR; PG8_MMA(1, 0, At, B0); PG8_MMA(1, 1, At, B1); PG8_BAR; PG8_SCHED;
.LBB0_620:
	v_add_u32_e32 v3, 0x10000, v199
	ds_read_b128 v[134:137], v3
	ds_read_b128 v[138:141], v3 offset:1024
	ds_read_b128 v[142:145], v3 offset:2048
	ds_read_b128 v[146:149], v3 offset:3072
	v_add_u32_e32 v3, 0x14000, v199
	s_add_u32 s44, s42, 0x100
	ds_read_b128 v[158:161], v3
	ds_read_b128 v[162:165], v3 offset:1024
	ds_read_b128 v[166:169], v3 offset:2048
	ds_read_b128 v[170:173], v3 offset:3072
	s_addc_u32 s45, s43, 0
	s_cmp_eq_u32 s92, 60
	s_cselect_b32 s56, s88, s44
	s_cselect_b32 s57, s23, s45
	s_cselect_b32 s47, s19, s91
	s_cselect_b32 s46, s89, s90
	s_add_u32 s50, s56, 0x80
	s_addc_u32 s51, s57, 0
	s_add_u32 s54, s46, 0x80
	s_addc_u32 s55, s47, 0
	ds_read_b128 v[174:177], v200
	ds_read_b128 v[178:181], v200 offset:1024
	ds_read_b128 v[182:185], v200 offset:2048
	ds_read_b128 v[186:189], v200 offset:3072
	ds_read_b128 v[190:193], v200 offset:4096
	ds_read_b128 v[202:205], v200 offset:5120
	ds_read_b128 v[206:209], v200 offset:6144
	ds_read_b128 v[210:213], v200 offset:7168
	s_add_u32 s42, s42, 0x100080
	s_addc_u32 s43, s43, 0
	s_mov_b32 m0, s85
	s_nop 0
	global_load_lds_dwordx4 v1, s[42:43]
	s_nop 0
	s_mov_b32 m0, s86
	s_nop 0
	global_load_lds_dwordx4 v195, s[42:43]
	s_waitcnt vmcnt(8)
	s_waitcnt lgkmcnt(0)
	s_barrier
	s_setprio 1
	s_waitcnt lgkmcnt(7)
	v_mfma_f32_16x16x32_bf16 v[62:65], v[170:173], v[178:181], v[62:65]
	v_mfma_f32_16x16x32_bf16 v[62:65], v[166:169], v[174:177], v[62:65]
	s_waitcnt lgkmcnt(5)
	v_mfma_f32_16x16x32_bf16 v[66:69], v[158:161], v[174:177], v[66:69]
	v_mfma_f32_16x16x32_bf16 v[66:69], v[162:165], v[178:181], v[66:69]
	s_waitcnt lgkmcnt(3)
	v_mfma_f32_16x16x32_bf16 v[126:129], v[146:149], v[178:181], v[126:129]
	v_mfma_f32_16x16x32_bf16 v[126:129], v[142:145], v[174:177], v[126:129]
	s_waitcnt lgkmcnt(1)
	v_mfma_f32_16x16x32_bf16 v[130:133], v[134:137], v[174:177], v[130:133]
	v_mfma_f32_16x16x32_bf16 v[130:133], v[138:141], v[178:181], v[130:133]
	v_mfma_f32_16x16x32_bf16 v[122:125], v[138:141], v[186:189], v[122:125]
	v_mfma_f32_16x16x32_bf16 v[122:125], v[134:137], v[182:185], v[122:125]
	v_mfma_f32_16x16x32_bf16 v[118:121], v[142:145], v[182:185], v[118:121]
	v_mfma_f32_16x16x32_bf16 v[118:121], v[146:149], v[186:189], v[118:121]
	v_mfma_f32_16x16x32_bf16 v[58:61], v[162:165], v[186:189], v[58:61]
	v_mfma_f32_16x16x32_bf16 v[58:61], v[158:161], v[182:185], v[58:61]
	s_waitcnt lgkmcnt(0)
	v_mfma_f32_16x16x32_bf16 v[54:57], v[166:169], v[182:185], v[54:57]
	v_mfma_f32_16x16x32_bf16 v[54:57], v[170:173], v[186:189], v[54:57]
	s_setprio 0
	s_setprio 1
	v_mfma_f32_16x16x32_bf16 v[46:49], v[170:173], v[202:205], v[46:49]
	v_mfma_f32_16x16x32_bf16 v[46:49], v[166:169], v[190:193], v[46:49]
	v_mfma_f32_16x16x32_bf16 v[50:53], v[158:161], v[190:193], v[50:53]
	v_mfma_f32_16x16x32_bf16 v[50:53], v[162:165], v[202:205], v[50:53]
	v_mfma_f32_16x16x32_bf16 v[110:113], v[146:149], v[202:205], v[110:113]
	v_mfma_f32_16x16x32_bf16 v[110:113], v[142:145], v[190:193], v[110:113]
	v_mfma_f32_16x16x32_bf16 v[114:117], v[134:137], v[190:193], v[114:117]
	v_mfma_f32_16x16x32_bf16 v[114:117], v[138:141], v[202:205], v[114:117]
	v_mfma_f32_16x16x32_bf16 v[106:109], v[138:141], v[210:213], v[106:109]
	v_mfma_f32_16x16x32_bf16 v[106:109], v[134:137], v[206:209], v[106:109]
	v_mfma_f32_16x16x32_bf16 v[102:105], v[142:145], v[206:209], v[102:105]
	v_mfma_f32_16x16x32_bf16 v[102:105], v[146:149], v[210:213], v[102:105]
	v_mfma_f32_16x16x32_bf16 v[42:45], v[162:165], v[210:213], v[42:45]
	v_mfma_f32_16x16x32_bf16 v[42:45], v[158:161], v[206:209], v[42:45]
	v_mfma_f32_16x16x32_bf16 v[38:41], v[166:169], v[206:209], v[38:41]
	s_setprio 2
	s_barrier
	v_mfma_f32_16x16x32_bf16 v[38:41], v[170:173], v[210:213], v[38:41]
	s_setprio 0
	ds_read_b128 v[174:177], v200 offset:16384
	ds_read_b128 v[178:181], v200 offset:17408
	ds_read_b128 v[182:185], v200 offset:18432
	ds_read_b128 v[186:189], v200 offset:19456
	ds_read_b128 v[190:193], v200 offset:20480
	ds_read_b128 v[202:205], v200 offset:21504
	ds_read_b128 v[206:209], v200 offset:22528
	ds_read_b128 v[252:255], v200 offset:23552
	s_mov_b32 m0, s63
	s_nop 0
	global_load_lds_dwordx4 v194, s[46:47]
	s_add_u32 s42, s46, 0x100000
	s_mov_b32 m0, s64
	s_nop 0
	global_load_lds_dwordx4 v196, s[46:47]
	s_addc_u32 s43, s47, 0
	s_mov_b32 m0, s65
	s_nop 0
	global_load_lds_dwordx4 v194, s[42:43]
	s_nop 0
	s_mov_b32 m0, s66
	s_nop 0
	global_load_lds_dwordx4 v196, s[42:43]
	s_nop 0
	s_mov_b32 m0, s62
	s_nop 0
	global_load_lds_dwordx4 v1, s[56:57]
	s_nop 0
	s_mov_b32 m0, s67
	s_nop 0
	global_load_lds_dwordx4 v195, s[56:57]
	s_waitcnt vmcnt(8)
	s_waitcnt lgkmcnt(0)
	s_barrier
; #define PG8_STAGE(bufoff, gbase, voff) do { _Pragma("unroll") for (int _i = 0; _i < 2; ++_i) \
;         asm volatile("s_mov_b32 m0, %2\n\ts_nop 0\n\tglobal_load_lds_dwordx4 %0, %1" :: "v"((voff)[_i]), "s"((const char*)(gbase)), "s"(ldsbase + (unsigned)(bufoff) + ldsw + (unsigned)_i * 8192u) : "memory", "m0"); } while (0)
; #define PG8_LDA(dst, b, h) do { _Pragma("unroll") for (int m = 0; m < 4; ++m) _Pragma("unroll") for (int k = 0; k < 2; ++k) dst[m][k] = *(const PG8_LAS bf16x8*)(lds + PG8_SA(b, h) + aoff + m * 2048 + k * 1024); } while (0)
; #define PG8_LDB(dst, b, h) do { _Pragma("unroll") for (int n = 0; n < 2; ++n) _Pragma("unroll") for (int k = 0; k < 2; ++k) dst[n][k] = *(const PG8_LAS bf16x8*)(lds + PG8_SB(b, h) + boff + n * 2048 + k * 1024); } while (0)
; #define PG8_MMA(ai, bj, At, Bt) do { __builtin_amdgcn_s_setprio(1); _Pragma("unroll") for (int m = 0; m < 4; ++m) _Pragma("unroll") for (int n = 0; n < 2; ++n) _Pragma("unroll") for (int k = 0; k < 2; ++k) \
;         acc[ai][bj][m][n] = __builtin_amdgcn_mfma_f32_16x16x32_bf16(Bt[n][k], At[m][k], acc[ai][bj][m][n], 0, 0, 0); __builtin_amdgcn_s_setprio(0); } while (0)
; #define PG8_WAIT_V(n) asm volatile("s_waitcnt vmcnt(" #n ")" ::: "memory")
; #define PG8_WAIT_L(n) asm volatile("s_waitcnt lgkmcnt(" #n ")" ::: "memory")
; #define PG8_BAR __builtin_amdgcn_s_barrier()
; #define PG8_SCHED __builtin_amdgcn_sched_barrier(0)
; template <class Epi, class Sched, bool ALIGN_EPI = false, bool SP2 = false>
; __device__ __forceinline__ void gemm_phase(PG8_LAS unsigned char* lds, const Gemm g, const Sched& S, const Epi& E) {
;     ...
;             PG8_WAIT_V(8); PG8_WAIT_L(0); PG8_BAR; PG8_MMA(1, 0, At, B0); PG8_MMA(1, 1, At, B1); PG8_BAR; PG8_SCHED;
;             PG8_LDB(B0, 1, 0); PG8_LDB(B1, 1, 1); PG8_SCHED; PG8_LDA(At, 1, 0); PG8_STAGE(PG8_SA(0, 1), a2 + hstep, voffA);
;             PG8_WAIT_V(8); PG8_WAIT_L(0); PG8_BAR; PG8_MMA(0, 0, At, B0); PG8_MMA(0, 1, At, B1); PG8_BAR; PG8_SCHED;
	s_setprio 1
	s_waitcnt lgkmcnt(7)
	v_mfma_f32_16x16x32_bf16 v[98:101], v[134:137], v[174:177], v[98:101]
	v_mfma_f32_16x16x32_bf16 v[94:97], v[142:145], v[174:177], v[94:97]
	s_waitcnt lgkmcnt(5)
	v_mfma_f32_16x16x32_bf16 v[90:93], v[134:137], v[182:185], v[90:93]
	v_mfma_f32_16x16x32_bf16 v[86:89], v[142:145], v[182:185], v[86:89]
	s_waitcnt lgkmcnt(3)
	v_mfma_f32_16x16x32_bf16 v[82:85], v[134:137], v[190:193], v[82:85]
	v_mfma_f32_16x16x32_bf16 v[78:81], v[142:145], v[190:193], v[78:81]
	s_waitcnt lgkmcnt(1)
	v_mfma_f32_16x16x32_bf16 v[74:77], v[134:137], v[206:209], v[74:77]
	v_mfma_f32_16x16x32_bf16 v[70:73], v[142:145], v[206:209], v[70:73]
	v_mfma_f32_16x16x32_bf16 v[98:101], v[138:141], v[178:181], v[98:101]
	v_mfma_f32_16x16x32_bf16 v[94:97], v[146:149], v[178:181], v[94:97]
	v_mfma_f32_16x16x32_bf16 v[90:93], v[138:141], v[186:189], v[90:93]
	v_mfma_f32_16x16x32_bf16 v[86:89], v[146:149], v[186:189], v[86:89]
	v_mfma_f32_16x16x32_bf16 v[82:85], v[138:141], v[202:205], v[82:85]
	v_mfma_f32_16x16x32_bf16 v[78:81], v[146:149], v[202:205], v[78:81]
	s_waitcnt lgkmcnt(0)
	v_mfma_f32_16x16x32_bf16 v[74:77], v[138:141], v[252:255], v[74:77]
	v_mfma_f32_16x16x32_bf16 v[70:73], v[146:149], v[252:255], v[70:73]
	s_setprio 0
	s_setprio 1
	v_mfma_f32_16x16x32_bf16 v[34:37], v[158:161], v[174:177], v[34:37]
	v_mfma_f32_16x16x32_bf16 v[30:33], v[166:169], v[174:177], v[30:33]
	v_mfma_f32_16x16x32_bf16 v[26:29], v[158:161], v[182:185], v[26:29]
	v_mfma_f32_16x16x32_bf16 v[22:25], v[166:169], v[182:185], v[22:25]
	v_mfma_f32_16x16x32_bf16 v[18:21], v[158:161], v[190:193], v[18:21]
	v_mfma_f32_16x16x32_bf16 v[14:17], v[166:169], v[190:193], v[14:17]
	v_mfma_f32_16x16x32_bf16 v[10:13], v[158:161], v[206:209], v[10:13]
	v_mfma_f32_16x16x32_bf16 v[4:7], v[166:169], v[206:209], v[6:9]
	v_mfma_f32_16x16x32_bf16 v[34:37], v[162:165], v[178:181], v[34:37]
	v_mfma_f32_16x16x32_bf16 v[30:33], v[170:173], v[178:181], v[30:33]
	v_mfma_f32_16x16x32_bf16 v[26:29], v[162:165], v[186:189], v[26:29]
	v_mfma_f32_16x16x32_bf16 v[22:25], v[170:173], v[186:189], v[22:25]
	v_mfma_f32_16x16x32_bf16 v[18:21], v[162:165], v[202:205], v[18:21]
	v_mfma_f32_16x16x32_bf16 v[14:17], v[170:173], v[202:205], v[14:17]
	v_mfma_f32_16x16x32_bf16 v[10:13], v[162:165], v[252:255], v[10:13]
	s_setprio 2
	s_barrier
	v_mfma_f32_16x16x32_bf16 v[4:7], v[170:173], v[252:255], v[4:7]
	s_setprio 0
	v_add_u32_e32 v3, 0x18000, v199
	ds_read_b128 v[134:137], v3
	ds_read_b128 v[138:141], v3 offset:1024
	ds_read_b128 v[142:145], v3 offset:2048
	ds_read_b128 v[146:149], v3 offset:3072
	v_add_u32_e32 v3, 0x1c000, v199
	ds_read_b128 v[158:161], v3
	ds_read_b128 v[162:165], v3 offset:1024
	ds_read_b128 v[166:169], v3 offset:2048
	ds_read_b128 v[248:251], v3 offset:3072
	ds_read_b128 v[174:177], v200 offset:32768
	ds_read_b128 v[178:181], v200 offset:33792
	ds_read_b128 v[182:185], v200 offset:34816
	ds_read_b128 v[186:189], v200 offset:35840
	ds_read_b128 v[190:193], v200 offset:36864
	ds_read_b128 v[202:205], v200 offset:37888
	ds_read_b128 v[206:209], v200 offset:38912
	ds_read_b128 v[210:213], v200 offset:39936
	s_add_u32 s42, s56, 0x100000
	s_addc_u32 s43, s57, 0
	s_mov_b32 m0, s76
	s_nop 0
	global_load_lds_dwordx4 v1, s[42:43]
	s_nop 0
	s_mov_b32 m0, s77
	s_nop 0
	global_load_lds_dwordx4 v195, s[42:43]
	s_waitcnt vmcnt(8)
	s_waitcnt lgkmcnt(0)
	s_barrier
	s_setprio 1
	s_waitcnt lgkmcnt(7)
	v_mfma_f32_16x16x32_bf16 v[62:65], v[248:251], v[178:181], v[62:65]
	v_mfma_f32_16x16x32_bf16 v[62:65], v[166:169], v[174:177], v[62:65]
	s_waitcnt lgkmcnt(5)
	v_mfma_f32_16x16x32_bf16 v[66:69], v[158:161], v[174:177], v[66:69]
	v_mfma_f32_16x16x32_bf16 v[66:69], v[162:165], v[178:181], v[66:69]
	s_waitcnt lgkmcnt(3)
	v_mfma_f32_16x16x32_bf16 v[126:129], v[146:149], v[178:181], v[126:129]
	v_mfma_f32_16x16x32_bf16 v[126:129], v[142:145], v[174:177], v[126:129]
	s_waitcnt lgkmcnt(1)
	v_mfma_f32_16x16x32_bf16 v[130:133], v[134:137], v[174:177], v[130:133]
	v_mfma_f32_16x16x32_bf16 v[130:133], v[138:141], v[178:181], v[130:133]
	v_mfma_f32_16x16x32_bf16 v[122:125], v[138:141], v[186:189], v[122:125]
	v_mfma_f32_16x16x32_bf16 v[122:125], v[134:137], v[182:185], v[122:125]
	v_mfma_f32_16x16x32_bf16 v[118:121], v[142:145], v[182:185], v[118:121]
	v_mfma_f32_16x16x32_bf16 v[118:121], v[146:149], v[186:189], v[118:121]
	v_mfma_f32_16x16x32_bf16 v[58:61], v[162:165], v[186:189], v[58:61]
	v_mfma_f32_16x16x32_bf16 v[58:61], v[158:161], v[182:185], v[58:61]
	s_waitcnt lgkmcnt(0)
	v_mfma_f32_16x16x32_bf16 v[54:57], v[166:169], v[182:185], v[54:57]
	v_mfma_f32_16x16x32_bf16 v[54:57], v[248:251], v[186:189], v[54:57]
	s_setprio 0
	s_setprio 1
	v_mfma_f32_16x16x32_bf16 v[46:49], v[248:251], v[202:205], v[46:49]
	v_mfma_f32_16x16x32_bf16 v[46:49], v[166:169], v[190:193], v[46:49]
	v_mfma_f32_16x16x32_bf16 v[50:53], v[158:161], v[190:193], v[50:53]
	v_mfma_f32_16x16x32_bf16 v[50:53], v[162:165], v[202:205], v[50:53]
	v_mfma_f32_16x16x32_bf16 v[110:113], v[146:149], v[202:205], v[110:113]
	v_mfma_f32_16x16x32_bf16 v[110:113], v[142:145], v[190:193], v[110:113]
	v_mfma_f32_16x16x32_bf16 v[114:117], v[134:137], v[190:193], v[114:117]
	v_mfma_f32_16x16x32_bf16 v[114:117], v[138:141], v[202:205], v[114:117]
	v_mfma_f32_16x16x32_bf16 v[106:109], v[138:141], v[210:213], v[106:109]
	v_mfma_f32_16x16x32_bf16 v[106:109], v[134:137], v[206:209], v[106:109]
	v_mfma_f32_16x16x32_bf16 v[102:105], v[142:145], v[206:209], v[102:105]
	v_mfma_f32_16x16x32_bf16 v[102:105], v[146:149], v[210:213], v[102:105]
	v_mfma_f32_16x16x32_bf16 v[42:45], v[162:165], v[210:213], v[42:45]
	v_mfma_f32_16x16x32_bf16 v[42:45], v[158:161], v[206:209], v[42:45]
	v_mfma_f32_16x16x32_bf16 v[38:41], v[166:169], v[206:209], v[38:41]
	s_setprio 2
	s_barrier
; #define PG8_STAGE(bufoff, gbase, voff) do { _Pragma("unroll") for (int _i = 0; _i < 2; ++_i) \
;         asm volatile("s_mov_b32 m0, %2\n\ts_nop 0\n\tglobal_load_lds_dwordx4 %0, %1" :: "v"((voff)[_i]), "s"((const char*)(gbase)), "s"(ldsbase + (unsigned)(bufoff) + ldsw + (unsigned)_i * 8192u) : "memory", "m0"); } while (0)
; #define PG8_LDA(dst, b, h) do { _Pragma("unroll") for (int m = 0; m < 4; ++m) _Pragma("unroll") for (int k = 0; k < 2; ++k) dst[m][k] = *(const PG8_LAS bf16x8*)(lds + PG8_SA(b, h) + aoff + m * 2048 + k * 1024); } while (0)
; #define PG8_MMA(ai, bj, At, Bt) do { __builtin_amdgcn_s_setprio(1); _Pragma("unroll") for (int m = 0; m < 4; ++m) _Pragma("unroll") for (int n = 0; n < 2; ++n) _Pragma("unroll") for (int k = 0; k < 2; ++k) \
;         acc[ai][bj][m][n] = __builtin_amdgcn_mfma_f32_16x16x32_bf16(Bt[n][k], At[m][k], acc[ai][bj][m][n], 0, 0, 0); __builtin_amdgcn_s_setprio(0); } while (0)
; #define PG8_WAIT_V(n) asm volatile("s_waitcnt vmcnt(" #n ")" ::: "memory")
; #define PG8_WAIT_L(n) asm volatile("s_waitcnt lgkmcnt(" #n ")" ::: "memory")
; #define PG8_BAR __builtin_amdgcn_s_barrier()
; #define PG8_SCHED __builtin_amdgcn_sched_barrier(0)
; template <class Epi, class Sched, bool ALIGN_EPI = false, bool SP2 = false>
; __device__ __forceinline__ void gemm_phase(PG8_LAS unsigned char* lds, const Gemm g, const Sched& S, const Epi& E) {
;     ...
;         for (int t = 0; t < nt; t += 2) {
;     ...
;             PG8_LDA(At, 1, 1); PG8_STAGE(PG8_SB(1, 0), b3, voffB); PG8_STAGE(PG8_SB(1, 1), b3 + hstep, voffB); PG8_STAGE(PG8_SA(1, 0), a3, voffA);
;             PG8_WAIT_V(8); PG8_WAIT_L(0); PG8_BAR; PG8_MMA(1, 0, At, B0); PG8_MMA(1, 1, At, B1); PG8_BAR; PG8_SCHED;
	v_mfma_f32_16x16x32_bf16 v[38:41], v[248:251], v[210:213], v[38:41]
	s_setprio 0
	ds_read_b128 v[174:177], v200 offset:49152
	ds_read_b128 v[178:181], v200 offset:50176
	ds_read_b128 v[182:185], v200 offset:51200
	ds_read_b128 v[186:189], v200 offset:52224
	ds_read_b128 v[190:193], v200 offset:53248
	ds_read_b128 v[202:205], v200 offset:54272
	ds_read_b128 v[206:209], v200 offset:55296
	ds_read_b128 v[252:255], v200 offset:56320
	s_mov_b32 m0, s78
	s_nop 0
	global_load_lds_dwordx4 v194, s[54:55]
	s_add_u32 s42, s46, 0x100080
	s_mov_b32 m0, s79
	s_nop 0
	global_load_lds_dwordx4 v196, s[54:55]
	s_addc_u32 s43, s47, 0
	s_mov_b32 m0, s83
	s_nop 0
	global_load_lds_dwordx4 v194, s[42:43]
	s_nop 0
	s_mov_b32 m0, s84
	s_nop 0
	global_load_lds_dwordx4 v196, s[42:43]
	s_nop 0
	s_mov_b32 m0, s80
	s_nop 0
	global_load_lds_dwordx4 v1, s[50:51]
	s_nop 0
	s_mov_b32 m0, s82
	s_nop 0
	global_load_lds_dwordx4 v195, s[50:51]
	s_waitcnt vmcnt(8)
	s_waitcnt lgkmcnt(0)
	s_barrier
	s_setprio 1
	s_waitcnt lgkmcnt(7)
	v_mfma_f32_16x16x32_bf16 v[98:101], v[134:137], v[174:177], v[98:101]
	v_mfma_f32_16x16x32_bf16 v[94:97], v[142:145], v[174:177], v[94:97]
	s_waitcnt lgkmcnt(5)
	v_mfma_f32_16x16x32_bf16 v[90:93], v[134:137], v[182:185], v[90:93]
	v_mfma_f32_16x16x32_bf16 v[86:89], v[142:145], v[182:185], v[86:89]
	s_waitcnt lgkmcnt(3)
	v_mfma_f32_16x16x32_bf16 v[82:85], v[134:137], v[190:193], v[82:85]
	v_mfma_f32_16x16x32_bf16 v[78:81], v[142:145], v[190:193], v[78:81]
	s_waitcnt lgkmcnt(1)
	v_mfma_f32_16x16x32_bf16 v[74:77], v[134:137], v[206:209], v[74:77]
	v_mfma_f32_16x16x32_bf16 v[70:73], v[142:145], v[206:209], v[70:73]
	v_mfma_f32_16x16x32_bf16 v[98:101], v[138:141], v[178:181], v[98:101]
	v_mfma_f32_16x16x32_bf16 v[94:97], v[146:149], v[178:181], v[94:97]
	v_mfma_f32_16x16x32_bf16 v[90:93], v[138:141], v[186:189], v[90:93]
	v_mfma_f32_16x16x32_bf16 v[86:89], v[146:149], v[186:189], v[86:89]
	v_mfma_f32_16x16x32_bf16 v[82:85], v[138:141], v[202:205], v[82:85]
	v_mfma_f32_16x16x32_bf16 v[78:81], v[146:149], v[202:205], v[78:81]
	s_waitcnt lgkmcnt(0)
	v_mfma_f32_16x16x32_bf16 v[74:77], v[138:141], v[252:255], v[74:77]
	v_mfma_f32_16x16x32_bf16 v[70:73], v[146:149], v[252:255], v[70:73]
	s_setprio 0
	s_setprio 1
	v_mfma_f32_16x16x32_bf16 v[34:37], v[158:161], v[174:177], v[34:37]
	v_mfma_f32_16x16x32_bf16 v[30:33], v[166:169], v[174:177], v[30:33]
	v_mfma_f32_16x16x32_bf16 v[26:29], v[158:161], v[182:185], v[26:29]
	v_mfma_f32_16x16x32_bf16 v[22:25], v[166:169], v[182:185], v[22:25]
	v_mfma_f32_16x16x32_bf16 v[18:21], v[158:161], v[190:193], v[18:21]
	v_mfma_f32_16x16x32_bf16 v[14:17], v[166:169], v[190:193], v[14:17]
	v_mfma_f32_16x16x32_bf16 v[8:11], v[158:161], v[206:209], v[10:13]
	v_mfma_f32_16x16x32_bf16 v[4:7], v[166:169], v[206:209], v[4:7]
	v_mfma_f32_16x16x32_bf16 v[34:37], v[162:165], v[178:181], v[34:37]
	v_mfma_f32_16x16x32_bf16 v[30:33], v[248:251], v[178:181], v[30:33]
	v_mfma_f32_16x16x32_bf16 v[26:29], v[162:165], v[186:189], v[26:29]
	v_mfma_f32_16x16x32_bf16 v[22:25], v[248:251], v[186:189], v[22:25]
	v_mfma_f32_16x16x32_bf16 v[18:21], v[162:165], v[202:205], v[18:21]
	v_mfma_f32_16x16x32_bf16 v[14:17], v[248:251], v[202:205], v[14:17]
	v_mfma_f32_16x16x32_bf16 v[10:13], v[162:165], v[252:255], v[8:11]
	v_mfma_f32_16x16x32_bf16 v[6:9], v[248:251], v[252:255], v[4:7]
	s_setprio 0
	s_barrier
	s_add_i32 s92, s92, 2
	s_add_u32 s90, s90, 0x100
	s_addc_u32 s91, s91, 0
	s_cmp_gt_u32 s92, 61
	s_cbranch_scc1 .LBB0_622
	s_mov_b64 s[42:43], s[44:45]
	s_cmp_lg_u32 s92, 30
	s_cbranch_scc0 .LBB0_619
	s_branch .LBB0_620
